# attention unit prologue: the vmcnt(0) hipcc placed between the 6th and 7th band-tile loads replaced by a counted wait at the first LDS write
# speedup vs baseline: 1.0037x; 1.0006x over previous
.LBB0_1654:
	s_bitcmp0_b32 s94, 0
	s_cselect_b32 s3, 1, -1
	s_and_b64 s[0:1], s[86:87], exec
	s_cselect_b32 s0, 0, s3
	s_add_i32 s72, s2, s0
	v_mov_b32_e32 v1, v178
	s_lshl_b32 s0, s72, 8
	v_readfirstlane_b32 s4, v1
	s_ashr_i32 s95, s4, 6
	s_ashr_i32 s1, s0, 31
	s_add_u32 s0, s74, s0
	s_addc_u32 s1, s75, s1
	s_lshl_b32 s96, s95, 5
	s_ashr_i32 s2, s96, 31
	s_add_u32 s0, s0, s96
	s_addc_u32 s1, s1, s2
	s_lshl_b64 s[0:1], s[0:1], 11
	v_readlane_b32 s2, v249, 28
	s_add_u32 s82, s2, s0
	v_readlane_b32 s0, v249, 12
	v_and_b32_e32 v157, 63, v1
	s_addc_u32 s83, s0, s1
	s_lshl_b32 s2, s95, 4
	v_bfe_u32 v2, v1, 2, 4
	v_or_b32_e32 v4, s74, v157
	v_mov_b32_e32 v5, s75
	v_and_or_b32 v2, s2, 48, v2
	v_lshlrev_b64 v[6:7], 11, v[4:5]
	v_or_b32_e32 v4, s74, v2
	v_readlane_b32 s2, v249, 54
	v_lshlrev_b64 v[4:5], 11, v[4:5]
	v_readlane_b32 s3, v249, 55
	v_lshlrev_b32_e32 v158, 3, v1
	v_and_b32_e32 v165, 24, v158
	v_lshl_add_u64 v[4:5], s[2:3], 0, v[4:5]
	s_ashr_i32 s2, s4, 3
	s_andn2_b32 s2, s2, 31
	s_ashr_i32 s3, s2, 31
	v_lshl_add_u64 v[4:5], s[2:3], 1, v[4:5]
	v_lshlrev_b32_e32 v2, 1, v165
	v_and_b32_e32 v159, 31, v1
	v_lshl_add_u64 v[152:153], v[4:5], 0, v[2:3]
	v_lshlrev_b32_e32 v2, 1, v1
	v_bfe_u32 v160, v1, 5, 1
	v_and_b32_e32 v166, 32, v2
	v_lshlrev_b32_e32 v2, 11, v159
	v_readlane_b32 s2, v249, 56
	s_lshl_b32 s0, s95, 3
	v_lshl_add_u64 v[4:5], s[82:83], 0, v[2:3]
	v_lshlrev_b32_e32 v2, 4, v160
	v_readlane_b32 s3, v249, 57
	s_lshl_b32 s84, s72, 2
	s_ashr_i32 s1, s0, 31
	v_lshl_add_u64 v[36:37], v[4:5], 0, v[2:3]
	v_lshl_add_u64 v[4:5], s[2:3], 0, v[6:7]
	s_ashr_i32 s85, s84, 31
	v_lshl_add_u64 v[154:155], s[0:1], 1, v[4:5]
	s_lshl_b64 s[0:1], s[84:85], 17
	v_lshl_add_u64 v[4:5], v[154:155], 0, s[0:1]
	global_load_dwordx4 v[4:7], v[4:5], off
	v_lshlrev_b32_e32 v163, 2, v160
	v_lshl_add_u64 v[8:9], v[152:153], 0, s[0:1]
	v_cmp_lt_u32_e32 vcc, v163, v159
	v_or_b32_e32 v161, 16, v163
	global_load_dwordx4 v[8:11], v[8:9], off
	v_cndmask_b32_e64 v2, v151, 0, vcc
	v_cmp_lt_u32_e32 vcc, v161, v159
	v_or_b32_e32 v146, 1, v163
	s_or_b32 s0, s84, 1
	v_bfe_u32 v169, v1, 2, 2
	v_cndmask_b32_e64 v39, v151, 0, vcc
	v_or_b32_e32 v1, 2, v163
	v_cmp_lt_u32_e32 vcc, v146, v159
	s_ashr_i32 s1, s0, 31
	v_or_b32_e32 v12, 17, v163
	v_cndmask_b32_e64 v40, v151, 0, vcc
	v_cmp_lt_u32_e32 vcc, v1, v159
	s_lshl_b64 s[2:3], s[0:1], 17
	v_or_b32_e32 v16, 18, v163
	v_cndmask_b32_e64 v41, v151, 0, vcc
	v_cmp_lt_u32_e32 vcc, v12, v159
	v_lshl_add_u64 v[12:13], v[154:155], 0, s[2:3]
	global_load_dwordx4 v[12:15], v[12:13], off
	v_cndmask_b32_e64 v42, v151, 0, vcc
	v_cmp_lt_u32_e32 vcc, v16, v159
	v_lshl_add_u64 v[16:17], v[152:153], 0, s[2:3]
	global_load_dwordx4 v[16:19], v[16:17], off
	s_or_b32 s2, s84, 2
	s_ashr_i32 s3, s2, 31
	s_lshl_b64 s[6:7], s[2:3], 17
	v_lshl_add_u64 v[20:21], v[154:155], 0, s[6:7]
	v_or_b32_e32 v148, 3, v163
	global_load_dwordx4 v[20:23], v[20:21], off
	v_cndmask_b32_e64 v43, v151, 0, vcc
	v_or_b32_e32 v147, 8, v163
	v_cmp_lt_u32_e32 vcc, v148, v159
	v_or_b32_e32 v25, 19, v163
	v_or_b32_e32 v24, 24, v163
	v_cndmask_b32_e64 v44, v151, 0, vcc
	v_cmp_lt_u32_e32 vcc, v147, v159
	s_mul_i32 s1, s72, 0x19c
	s_sext_i32_i16 s3, s1
	v_cndmask_b32_e64 v45, v151, 0, vcc
	v_cmp_lt_u32_e32 vcc, v25, v159
	s_lshr_b32 s3, s3, 9
	s_bfe_u32 s1, s1, 0x1000f
	v_cndmask_b32_e64 v46, v151, 0, vcc
	v_cmp_lt_u32_e32 vcc, v24, v159
	v_lshl_add_u64 v[24:25], v[152:153], 0, s[6:7]
	global_load_dwordx4 v[24:27], v[24:25], off
	s_or_b32 s6, s84, 3
	s_ashr_i32 s7, s6, 31
	s_lshl_b64 s[8:9], s[6:7], 17
	s_nop 0
	v_lshl_add_u64 v[28:29], v[154:155], 0, s[8:9]
	global_load_dwordx4 v[28:31], v[28:29], off
	v_lshl_add_u64 v[32:33], v[152:153], 0, s[8:9]
	global_load_dwordx4 v[32:35], v[32:33], off
	s_nop 0
	global_load_dwordx4 v[114:117], v[36:37], off offset:96
	global_load_dwordx4 v[118:121], v[36:37], off offset:64
	global_load_dwordx4 v[122:125], v[36:37], off offset:32
	global_load_dwordx4 v[126:129], v[36:37], off
	s_add_i32 s1, s3, s1
	v_lshlrev_b32_e32 v38, 4, v157
	s_mul_i32 s1, s1, 5
	v_lshl_or_b32 v170, s95, 10, v38
	s_sub_i32 s1, s84, s1
	v_add_u32_e32 v38, 0, v170
	s_sext_i32_i8 s1, s1
	v_lshl_add_u32 v52, s1, 13, v38
	s_mul_i32 s1, s72, 0xac
	s_bfe_u32 s3, s1, 0x1000f
	s_bfe_u32 s1, s1, 0x80008
	s_add_i32 s1, s1, s3
	s_mul_i32 s1, s1, 6
	s_sub_i32 s1, s84, s1
	s_sext_i32_i8 s1, s1
	v_or_b32_e32 v149, 10, v163
	v_cndmask_b32_e64 v47, v151, 0, vcc
	v_or_b32_e32 v150, 9, v163
	v_cmp_lt_u32_e32 vcc, v149, v159
	v_or_b32_e32 v50, 26, v163
	v_or_b32_e32 v51, 25, v163
	s_waitcnt vmcnt(6)
	ds_write_b128 v52, v[4:7]
	v_lshl_add_u32 v4, s1, 13, v38
	s_mul_hi_i32 s1, s0, 0x66666667
	s_lshr_b32 s3, s1, 31
	s_lshr_b32 s1, s1, 1
	s_add_i32 s1, s1, s3
	s_mul_i32 s1, s1, 5
	s_sub_i32 s1, s0, s1
	ds_write_b128 v4, v[8:11] offset:40960
	v_lshl_add_u32 v4, s1, 13, v38
	s_mul_hi_i32 s1, s0, 0x2aaaaaab
	s_lshr_b32 s3, s1, 31
	s_add_i32 s1, s1, s3
	s_mul_i32 s1, s1, 6
	s_sub_i32 s0, s0, s1
	v_cndmask_b32_e64 v48, v151, 0, vcc
	v_cmp_lt_u32_e32 vcc, v150, v159
	s_ashr_i32 s85, s4, 7
	v_or_b32_e32 v162, 11, v163
	v_cndmask_b32_e64 v49, v151, 0, vcc
	v_cmp_lt_u32_e32 vcc, v50, v159
	s_add_i32 s76, s85, s84
	v_or_b32_e32 v37, 27, v163
	ds_write_b128 v4, v[12:15]
	v_lshl_add_u32 v4, s0, 13, v38
	s_mul_hi_i32 s0, s2, 0x66666667
	s_lshr_b32 s1, s0, 31
	s_lshr_b32 s0, s0, 1
	s_add_i32 s0, s0, s1
	s_mul_i32 s0, s0, 5
	s_sub_i32 s0, s2, s0
	ds_write_b128 v4, v[16:19] offset:40960
	v_lshl_add_u32 v4, s0, 13, v38
	s_mul_hi_i32 s0, s2, 0x2aaaaaab
	s_lshr_b32 s1, s0, 31
	s_add_i32 s0, s0, s1
	s_mul_i32 s0, s0, 6
	s_sub_i32 s0, s2, s0
	ds_write_b128 v4, v[20:23]
	v_lshl_add_u32 v4, s0, 13, v38
	s_mul_hi_i32 s0, s6, 0x66666667
	s_lshr_b32 s1, s0, 31
	s_lshr_b32 s0, s0, 1
	s_add_i32 s0, s0, s1
	s_mul_i32 s0, s0, 5
	s_sub_i32 s0, s6, s0
	v_cndmask_b32_e64 v50, v151, 0, vcc
	v_cmp_lt_u32_e32 vcc, v51, v159
	v_pack_b32_f16 v130, v2, v40
	v_lshlrev_b32_e32 v167, 10, v160
	ds_write_b128 v4, v[24:27] offset:40960
	v_lshl_add_u32 v4, s0, 13, v38
	s_mul_hi_i32 s0, s6, 0x2aaaaaab
	s_lshr_b32 s1, s0, 31
	s_add_i32 s0, s0, s1
	s_mul_i32 s0, s0, 6
	s_sub_i32 s0, s6, s0
	s_waitcnt vmcnt(5)
	ds_write_b128 v4, v[28:31]
	v_lshl_add_u32 v4, s0, 13, v38
	s_lshl_b32 s0, s95, 2
	s_add_i32 s33, s0, 0
	s_add_i32 s33, s33, 0x1e000
	v_cndmask_b32_e64 v51, v151, 0, vcc
	v_cmp_lt_u32_e32 vcc, v162, v159
	s_cmp_lg_u32 s84, -4
	s_cselect_b64 s[2:3], -1, 0
	v_cndmask_b32_e64 v36, v151, 0, vcc
	v_cmp_lt_u32_e32 vcc, v37, v159
	v_cndmask_b32_e64 v2, 0, 1, s[2:3]
	v_lshlrev_b32_e32 v168, 4, v159
	v_cndmask_b32_e64 v37, v151, 0, vcc
	v_pack_b32_f16 v132, v45, v49
	v_pack_b32_f16 v131, v41, v44
	v_pack_b32_f16 v133, v48, v36
	v_pack_b32_f16 v136, v47, v51
	v_pack_b32_f16 v135, v43, v46
	v_pack_b32_f16 v137, v50, v37
	v_pack_b32_f16 v134, v39, v42
	v_or_b32_e32 v164, s96, v159
	s_cmp_lt_i32 s95, 4
	s_mov_b64 s[0:1], -1
	v_cmp_ne_u32_e64 s[2:3], 1, v2
	s_waitcnt vmcnt(4)
	ds_write_b128 v4, v[32:35] offset:40960
	s_waitcnt vmcnt(0)
	s_waitcnt lgkmcnt(0)
	s_barrier
	s_cbranch_scc1 .LBB0_1674
	v_readlane_b32 s0, v249, 52
	v_or_b32_e32 v4, v163, v169
	v_lshlrev_b32_e32 v4, 6, v4
	v_add_u32_e32 v2, s0, v166
	v_add3_u32 v171, v2, v165, v4
	s_and_b64 vcc, exec, s[2:3]
	s_mov_b32 s73, 0
	s_cbranch_vccnz .LBB0_1689
	s_lshl_b32 s0, s85, 6
	s_lshl_b32 s81, s85, 13
	s_or_b32 s92, s0, 63
	v_readlane_b32 s0, v249, 60
	v_or_b32_e32 v2, s81, v167
	v_mov_b32_e32 v16, v3
	v_mov_b32_e32 v17, v3
	v_mov_b32_e32 v68, v3
	v_mov_b32_e32 v69, v3
	v_add_u32_e32 v172, s0, v170
	v_readlane_b32 s0, v249, 62
	v_add3_u32 v174, v2, v168, 0
	v_mov_b32_e32 v2, v3
	v_mov_b32_e32 v4, v3
	v_mov_b32_e32 v5, v3
	v_mov_b32_e32 v6, v3
	v_mov_b32_e32 v7, v3
	v_mov_b32_e32 v8, v3
	v_mov_b32_e32 v9, v3
	v_mov_b32_e32 v10, v3
	v_mov_b32_e32 v11, v3
	v_mov_b32_e32 v12, v3
	v_mov_b32_e32 v13, v3
	v_mov_b32_e32 v14, v3
	v_mov_b32_e32 v15, v3
	v_mov_b32_e32 v66, v3
	v_mov_b32_e32 v67, v3
	v_mov_b32_e32 v18, 0
	v_mov_b64_e32 v[76:77], v[68:69]
	v_mov_b64_e32 v[84:85], v[68:69]
	v_mov_b64_e32 v[72:73], v[68:69]
	v_mov_b64_e32 v[64:65], v[16:17]
	v_cmp_eq_u32_e64 s[4:5], 0, v157
	s_lshl_b32 s93, s72, 15
	s_add_i32 s80, s84, -1
	v_add_u32_e32 v173, s0, v170
	s_mov_b64 s[0:1], 0
	s_mov_b32 s97, s76
	s_mov_b32 s77, 0
	s_mov_b32 s78, s84
	s_mov_b64 s[6:7], 0
	s_mov_b32 s8, 0
	v_mov_b64_e32 v[74:75], v[66:67]
	v_mov_b64_e32 v[82:83], v[66:67]
	v_mov_b64_e32 v[70:71], v[66:67]
	v_mov_b64_e32 v[62:63], v[14:15]
	v_mov_b64_e32 v[60:61], v[12:13]
	v_mov_b64_e32 v[58:59], v[10:11]
	v_mov_b64_e32 v[56:57], v[8:9]
	v_mov_b64_e32 v[54:55], v[6:7]
	v_mov_b64_e32 v[52:53], v[4:5]
	v_mov_b64_e32 v[50:51], v[2:3]
	v_mov_b32_e32 v19, v18
	v_mov_b32_e32 v20, v18
	v_mov_b32_e32 v21, v18
	v_mov_b32_e32 v22, v18
	v_mov_b32_e32 v23, v18
	v_mov_b32_e32 v24, v18
	v_mov_b32_e32 v25, v18
	v_mov_b32_e32 v26, v18
	v_mov_b32_e32 v27, v18
	v_mov_b32_e32 v28, v18
	v_mov_b32_e32 v29, v18
	v_mov_b32_e32 v30, v18
	v_mov_b32_e32 v31, v18
	v_mov_b32_e32 v32, v18
	v_mov_b32_e32 v33, v18
	v_mov_b32_e32 v34, v18
	v_mov_b32_e32 v35, v18
	v_mov_b32_e32 v36, v18
	v_mov_b32_e32 v37, v18
	v_mov_b32_e32 v38, v18
	v_mov_b32_e32 v39, v18
	v_mov_b32_e32 v40, v18
	v_mov_b32_e32 v41, v18
	v_mov_b32_e32 v42, v18
	v_mov_b32_e32 v43, v18
	v_mov_b32_e32 v44, v18
	v_mov_b32_e32 v45, v18
	v_mov_b32_e32 v46, v18
	v_mov_b32_e32 v47, v18
	v_mov_b32_e32 v48, v18
	v_mov_b32_e32 v49, v18
